# phase C residual epilogue: nt (streaming) hint on the f32 residual loads and stores
# baseline (speedup 1.0000x reference)
.LBB0_161:
	v_lshrrev_b32_e32 v60, 5, v78
	v_mul_u32_u24_e32 v61, 0x210, v60
	v_lshl_add_u32 v61, v79, 4, v61
	v_add_u32_e32 v62, 0x10800, v61
	v_add_u32_e32 v63, s22, v60
	v_lshlrev_b32_e32 v98, 10, v63
	v_add_u32_e32 v98, s31, v98
	v_lshl_add_u32 v98, v79, 2, v98
	v_lshlrev_b32_e32 v98, 2, v98
	v_lshlrev_b32_e32 v99, 2, v63
	v_xor_b32_e32 v182, 16, v192
	v_lshlrev_b32_e32 v182, 2, v182
	s_add_u32 s20, s94, 0x2500000
	s_addc_u32 s21, s95, 0
	s_and_b64 vcc, exec, s[44:45]
	s_cbranch_vccz .Lcepi_last
	ds_read_b128 v[12:15], v61 offset:0
	v_mov_b32_e32 v134, v98
	global_load_dwordx4 v[100:103], v134, s[92:93] nt
	ds_read_b128 v[16:19], v61 offset:8448
	v_add_u32_e32 v135, 0x10000, v98
	global_load_dwordx4 v[104:107], v135, s[92:93] nt
	ds_read_b128 v[20:23], v61 offset:16896
	v_add_u32_e32 v136, 0x20000, v98
	global_load_dwordx4 v[108:111], v136, s[92:93] nt
	ds_read_b128 v[24:27], v61 offset:25344
	v_add_u32_e32 v137, 0x30000, v98
	global_load_dwordx4 v[112:115], v137, s[92:93] nt
	ds_read_b128 v[28:31], v61 offset:33792
	v_add_u32_e32 v138, 0x40000, v98
	global_load_dwordx4 v[116:119], v138, s[92:93] nt
	ds_read_b128 v[32:35], v61 offset:42240
	v_add_u32_e32 v139, 0x50000, v98
	global_load_dwordx4 v[120:123], v139, s[92:93] nt
	ds_read_b128 v[36:39], v61 offset:50688
	v_add_u32_e32 v140, 0x60000, v98
	global_load_dwordx4 v[124:127], v140, s[92:93] nt
	ds_read_b128 v[40:43], v61 offset:59136
	v_add_u32_e32 v141, 0x70000, v98
	global_load_dwordx4 v[128:131], v141, s[92:93] nt
	s_waitcnt vmcnt(7) lgkmcnt(7)
	v_pk_add_f32 v[100:101], v[100:101], v[12:13]
	v_pk_add_f32 v[102:103], v[102:103], v[14:15]
	global_store_dwordx4 v134, v[100:103], s[92:93] nt
	v_cvt_pk_bf16_f32 v12, v100, v101
	v_cvt_pk_bf16_f32 v13, v102, v103
	v_lshrrev_b32_e32 v14, 1, v134
	v_pk_mul_f32 v[100:101], v[100:101], v[100:101]
	v_pk_mul_f32 v[102:103], v[102:103], v[102:103]
	global_store_dwordx2 v14, v[12:13], s[20:21]
	v_add_f32_e32 v100, v100, v101
	v_add_f32_e32 v102, v102, v103
	v_add_f32_e32 v142, v100, v102
	s_waitcnt vmcnt(8) lgkmcnt(6)
	v_pk_add_f32 v[104:105], v[104:105], v[16:17]
	v_pk_add_f32 v[106:107], v[106:107], v[18:19]
	global_store_dwordx4 v135, v[104:107], s[92:93] nt
	v_cvt_pk_bf16_f32 v16, v104, v105
	v_cvt_pk_bf16_f32 v17, v106, v107
	v_lshrrev_b32_e32 v18, 1, v135
	v_pk_mul_f32 v[104:105], v[104:105], v[104:105]
	v_pk_mul_f32 v[106:107], v[106:107], v[106:107]
	global_store_dwordx2 v18, v[16:17], s[20:21]
	v_add_f32_e32 v104, v104, v105
	v_add_f32_e32 v106, v106, v107
	v_add_f32_e32 v143, v104, v106
	s_waitcnt vmcnt(9) lgkmcnt(5)
	v_pk_add_f32 v[108:109], v[108:109], v[20:21]
	v_pk_add_f32 v[110:111], v[110:111], v[22:23]
	global_store_dwordx4 v136, v[108:111], s[92:93] nt
	v_cvt_pk_bf16_f32 v20, v108, v109
	v_cvt_pk_bf16_f32 v21, v110, v111
	v_lshrrev_b32_e32 v22, 1, v136
	v_pk_mul_f32 v[108:109], v[108:109], v[108:109]
	v_pk_mul_f32 v[110:111], v[110:111], v[110:111]
	global_store_dwordx2 v22, v[20:21], s[20:21]
	v_add_f32_e32 v108, v108, v109
	v_add_f32_e32 v110, v110, v111
	v_add_f32_e32 v144, v108, v110
	s_waitcnt vmcnt(10) lgkmcnt(4)
	v_pk_add_f32 v[112:113], v[112:113], v[24:25]
	v_pk_add_f32 v[114:115], v[114:115], v[26:27]
	global_store_dwordx4 v137, v[112:115], s[92:93] nt
	v_cvt_pk_bf16_f32 v24, v112, v113
	v_cvt_pk_bf16_f32 v25, v114, v115
	v_lshrrev_b32_e32 v26, 1, v137
	v_pk_mul_f32 v[112:113], v[112:113], v[112:113]
	v_pk_mul_f32 v[114:115], v[114:115], v[114:115]
	global_store_dwordx2 v26, v[24:25], s[20:21]
	v_add_f32_e32 v112, v112, v113
	v_add_f32_e32 v114, v114, v115
	v_add_f32_e32 v145, v112, v114
	s_waitcnt vmcnt(11) lgkmcnt(3)
	v_pk_add_f32 v[116:117], v[116:117], v[28:29]
	v_pk_add_f32 v[118:119], v[118:119], v[30:31]
	global_store_dwordx4 v138, v[116:119], s[92:93] nt
	v_cvt_pk_bf16_f32 v28, v116, v117
	v_cvt_pk_bf16_f32 v29, v118, v119
	v_lshrrev_b32_e32 v30, 1, v138
	v_pk_mul_f32 v[116:117], v[116:117], v[116:117]
	v_pk_mul_f32 v[118:119], v[118:119], v[118:119]
	global_store_dwordx2 v30, v[28:29], s[20:21]
	v_add_f32_e32 v116, v116, v117
	v_add_f32_e32 v118, v118, v119
	v_add_f32_e32 v146, v116, v118
	s_waitcnt vmcnt(12) lgkmcnt(2)
	v_pk_add_f32 v[120:121], v[120:121], v[32:33]
	v_pk_add_f32 v[122:123], v[122:123], v[34:35]
	global_store_dwordx4 v139, v[120:123], s[92:93] nt
	v_cvt_pk_bf16_f32 v32, v120, v121
	v_cvt_pk_bf16_f32 v33, v122, v123
	v_lshrrev_b32_e32 v34, 1, v139
	v_pk_mul_f32 v[120:121], v[120:121], v[120:121]
	v_pk_mul_f32 v[122:123], v[122:123], v[122:123]
	global_store_dwordx2 v34, v[32:33], s[20:21]
	v_add_f32_e32 v120, v120, v121
	v_add_f32_e32 v122, v122, v123
	v_add_f32_e32 v147, v120, v122
	s_waitcnt vmcnt(13) lgkmcnt(1)
	v_pk_add_f32 v[124:125], v[124:125], v[36:37]
	v_pk_add_f32 v[126:127], v[126:127], v[38:39]
	global_store_dwordx4 v140, v[124:127], s[92:93] nt
	v_cvt_pk_bf16_f32 v36, v124, v125
	v_cvt_pk_bf16_f32 v37, v126, v127
	v_lshrrev_b32_e32 v38, 1, v140
	v_pk_mul_f32 v[124:125], v[124:125], v[124:125]
	v_pk_mul_f32 v[126:127], v[126:127], v[126:127]
	global_store_dwordx2 v38, v[36:37], s[20:21]
	v_add_f32_e32 v124, v124, v125
	v_add_f32_e32 v126, v126, v127
	v_add_f32_e32 v148, v124, v126
	s_waitcnt vmcnt(14) lgkmcnt(0)
	v_pk_add_f32 v[128:129], v[128:129], v[40:41]
	v_pk_add_f32 v[130:131], v[130:131], v[42:43]
	global_store_dwordx4 v141, v[128:131], s[92:93] nt
	v_cvt_pk_bf16_f32 v40, v128, v129
	v_cvt_pk_bf16_f32 v41, v130, v131
	v_lshrrev_b32_e32 v42, 1, v141
	v_pk_mul_f32 v[128:129], v[128:129], v[128:129]
	v_pk_mul_f32 v[130:131], v[130:131], v[130:131]
	global_store_dwordx2 v42, v[40:41], s[20:21]
	v_add_f32_e32 v128, v128, v129
	v_add_f32_e32 v130, v130, v131
	v_add_f32_e32 v149, v128, v130
	v_add_f32_dpp v142, v142, v142 quad_perm:[1,0,3,2] row_mask:0xf bank_mask:0xf bound_ctrl:1
	v_add_f32_dpp v143, v143, v143 quad_perm:[1,0,3,2] row_mask:0xf bank_mask:0xf bound_ctrl:1
	v_add_f32_dpp v144, v144, v144 quad_perm:[1,0,3,2] row_mask:0xf bank_mask:0xf bound_ctrl:1
	v_add_f32_dpp v145, v145, v145 quad_perm:[1,0,3,2] row_mask:0xf bank_mask:0xf bound_ctrl:1
	v_add_f32_dpp v146, v146, v146 quad_perm:[1,0,3,2] row_mask:0xf bank_mask:0xf bound_ctrl:1
	v_add_f32_dpp v147, v147, v147 quad_perm:[1,0,3,2] row_mask:0xf bank_mask:0xf bound_ctrl:1
	v_add_f32_dpp v148, v148, v148 quad_perm:[1,0,3,2] row_mask:0xf bank_mask:0xf bound_ctrl:1
	v_add_f32_dpp v149, v149, v149 quad_perm:[1,0,3,2] row_mask:0xf bank_mask:0xf bound_ctrl:1
	v_add_f32_dpp v142, v142, v142 quad_perm:[2,3,0,1] row_mask:0xf bank_mask:0xf bound_ctrl:1
	v_add_f32_dpp v143, v143, v143 quad_perm:[2,3,0,1] row_mask:0xf bank_mask:0xf bound_ctrl:1
	v_add_f32_dpp v144, v144, v144 quad_perm:[2,3,0,1] row_mask:0xf bank_mask:0xf bound_ctrl:1
	v_add_f32_dpp v145, v145, v145 quad_perm:[2,3,0,1] row_mask:0xf bank_mask:0xf bound_ctrl:1
	v_add_f32_dpp v146, v146, v146 quad_perm:[2,3,0,1] row_mask:0xf bank_mask:0xf bound_ctrl:1
	v_add_f32_dpp v147, v147, v147 quad_perm:[2,3,0,1] row_mask:0xf bank_mask:0xf bound_ctrl:1
	v_add_f32_dpp v148, v148, v148 quad_perm:[2,3,0,1] row_mask:0xf bank_mask:0xf bound_ctrl:1
	v_add_f32_dpp v149, v149, v149 quad_perm:[2,3,0,1] row_mask:0xf bank_mask:0xf bound_ctrl:1
	v_add_f32_dpp v142, v142, v142 row_half_mirror row_mask:0xf bank_mask:0xf bound_ctrl:1
	v_add_f32_dpp v143, v143, v143 row_half_mirror row_mask:0xf bank_mask:0xf bound_ctrl:1
	v_add_f32_dpp v144, v144, v144 row_half_mirror row_mask:0xf bank_mask:0xf bound_ctrl:1
	v_add_f32_dpp v145, v145, v145 row_half_mirror row_mask:0xf bank_mask:0xf bound_ctrl:1
	v_add_f32_dpp v146, v146, v146 row_half_mirror row_mask:0xf bank_mask:0xf bound_ctrl:1
	v_add_f32_dpp v147, v147, v147 row_half_mirror row_mask:0xf bank_mask:0xf bound_ctrl:1
	v_add_f32_dpp v148, v148, v148 row_half_mirror row_mask:0xf bank_mask:0xf bound_ctrl:1
	v_add_f32_dpp v149, v149, v149 row_half_mirror row_mask:0xf bank_mask:0xf bound_ctrl:1
	v_add_f32_dpp v142, v142, v142 row_mirror row_mask:0xf bank_mask:0xf bound_ctrl:1
	v_add_f32_dpp v143, v143, v143 row_mirror row_mask:0xf bank_mask:0xf bound_ctrl:1
	v_add_f32_dpp v144, v144, v144 row_mirror row_mask:0xf bank_mask:0xf bound_ctrl:1
	v_add_f32_dpp v145, v145, v145 row_mirror row_mask:0xf bank_mask:0xf bound_ctrl:1
	v_add_f32_dpp v146, v146, v146 row_mirror row_mask:0xf bank_mask:0xf bound_ctrl:1
	v_add_f32_dpp v147, v147, v147 row_mirror row_mask:0xf bank_mask:0xf bound_ctrl:1
	v_add_f32_dpp v148, v148, v148 row_mirror row_mask:0xf bank_mask:0xf bound_ctrl:1
	v_add_f32_dpp v149, v149, v149 row_mirror row_mask:0xf bank_mask:0xf bound_ctrl:1
	ds_bpermute_b32 v12, v182, v142
	ds_bpermute_b32 v16, v182, v143
	ds_bpermute_b32 v20, v182, v144
	ds_bpermute_b32 v24, v182, v145
	ds_bpermute_b32 v28, v182, v146
	ds_bpermute_b32 v32, v182, v147
	ds_bpermute_b32 v36, v182, v148
	ds_bpermute_b32 v40, v182, v149
	s_waitcnt lgkmcnt(0)
	v_add_f32_e32 v142, v142, v12
	v_add_f32_e32 v143, v143, v16
	v_add_f32_e32 v144, v144, v20
	v_add_f32_e32 v145, v145, v24
	v_add_f32_e32 v146, v146, v28
	v_add_f32_e32 v147, v147, v32
	v_add_f32_e32 v148, v148, v36
	v_add_f32_e32 v149, v149, v40
	v_add_u32_e32 v13, 0x0, v99
	v_add_u32_e32 v17, 0x40, v99
	v_add_u32_e32 v21, 0x80, v99
	v_add_u32_e32 v25, 0xc0, v99
	v_add_u32_e32 v29, 0x100, v99
	v_add_u32_e32 v33, 0x140, v99
	v_add_u32_e32 v37, 0x180, v99
	v_add_u32_e32 v41, 0x1c0, v99
	s_mov_b64 exec, s[0:1]
	global_atomic_add_f32 v13, v142, s[50:51]
	global_atomic_add_f32 v17, v143, s[50:51]
	global_atomic_add_f32 v21, v144, s[50:51]
	global_atomic_add_f32 v25, v145, s[50:51]
	global_atomic_add_f32 v29, v146, s[50:51]
	global_atomic_add_f32 v33, v147, s[50:51]
	global_atomic_add_f32 v37, v148, s[50:51]
	global_atomic_add_f32 v41, v149, s[50:51]
	s_mov_b64 exec, -1
	ds_read_b128 v[12:15], v62 offset:0
	v_add_u32_e32 v134, 0x80000, v98
	global_load_dwordx4 v[100:103], v134, s[92:93] nt
	ds_read_b128 v[16:19], v62 offset:8448
	v_add_u32_e32 v135, 0x90000, v98
	global_load_dwordx4 v[104:107], v135, s[92:93] nt
	ds_read_b128 v[20:23], v62 offset:16896
	v_add_u32_e32 v136, 0xa0000, v98
	global_load_dwordx4 v[108:111], v136, s[92:93] nt
	ds_read_b128 v[24:27], v62 offset:25344
	v_add_u32_e32 v137, 0xb0000, v98
	global_load_dwordx4 v[112:115], v137, s[92:93] nt
	ds_read_b128 v[28:31], v62 offset:33792
	v_add_u32_e32 v138, 0xc0000, v98
	global_load_dwordx4 v[116:119], v138, s[92:93] nt
	ds_read_b128 v[32:35], v62 offset:42240
	v_add_u32_e32 v139, 0xd0000, v98
	global_load_dwordx4 v[120:123], v139, s[92:93] nt
	ds_read_b128 v[36:39], v62 offset:50688
	v_add_u32_e32 v140, 0xe0000, v98
	global_load_dwordx4 v[124:127], v140, s[92:93] nt
	ds_read_b128 v[40:43], v62 offset:59136
	v_add_u32_e32 v141, 0xf0000, v98
	global_load_dwordx4 v[128:131], v141, s[92:93] nt
	s_waitcnt vmcnt(7) lgkmcnt(7)
	v_pk_add_f32 v[100:101], v[100:101], v[12:13]
	v_pk_add_f32 v[102:103], v[102:103], v[14:15]
	global_store_dwordx4 v134, v[100:103], s[92:93] nt
	v_cvt_pk_bf16_f32 v12, v100, v101
	v_cvt_pk_bf16_f32 v13, v102, v103
	v_lshrrev_b32_e32 v14, 1, v134
	v_pk_mul_f32 v[100:101], v[100:101], v[100:101]
	v_pk_mul_f32 v[102:103], v[102:103], v[102:103]
	global_store_dwordx2 v14, v[12:13], s[20:21]
	v_add_f32_e32 v100, v100, v101
	v_add_f32_e32 v102, v102, v103
	v_add_f32_e32 v142, v100, v102
	s_waitcnt vmcnt(8) lgkmcnt(6)
	v_pk_add_f32 v[104:105], v[104:105], v[16:17]
	v_pk_add_f32 v[106:107], v[106:107], v[18:19]
	global_store_dwordx4 v135, v[104:107], s[92:93] nt
	v_cvt_pk_bf16_f32 v16, v104, v105
	v_cvt_pk_bf16_f32 v17, v106, v107
	v_lshrrev_b32_e32 v18, 1, v135
	v_pk_mul_f32 v[104:105], v[104:105], v[104:105]
	v_pk_mul_f32 v[106:107], v[106:107], v[106:107]
	global_store_dwordx2 v18, v[16:17], s[20:21]
	v_add_f32_e32 v104, v104, v105
	v_add_f32_e32 v106, v106, v107
	v_add_f32_e32 v143, v104, v106
	s_waitcnt vmcnt(9) lgkmcnt(5)
	v_pk_add_f32 v[108:109], v[108:109], v[20:21]
	v_pk_add_f32 v[110:111], v[110:111], v[22:23]
	global_store_dwordx4 v136, v[108:111], s[92:93] nt
	v_cvt_pk_bf16_f32 v20, v108, v109
	v_cvt_pk_bf16_f32 v21, v110, v111
	v_lshrrev_b32_e32 v22, 1, v136
	v_pk_mul_f32 v[108:109], v[108:109], v[108:109]
	v_pk_mul_f32 v[110:111], v[110:111], v[110:111]
	global_store_dwordx2 v22, v[20:21], s[20:21]
	v_add_f32_e32 v108, v108, v109
	v_add_f32_e32 v110, v110, v111
	v_add_f32_e32 v144, v108, v110
	s_waitcnt vmcnt(10) lgkmcnt(4)
	v_pk_add_f32 v[112:113], v[112:113], v[24:25]
	v_pk_add_f32 v[114:115], v[114:115], v[26:27]
	global_store_dwordx4 v137, v[112:115], s[92:93] nt
	v_cvt_pk_bf16_f32 v24, v112, v113
	v_cvt_pk_bf16_f32 v25, v114, v115
	v_lshrrev_b32_e32 v26, 1, v137
	v_pk_mul_f32 v[112:113], v[112:113], v[112:113]
	v_pk_mul_f32 v[114:115], v[114:115], v[114:115]
	global_store_dwordx2 v26, v[24:25], s[20:21]
	v_add_f32_e32 v112, v112, v113
	v_add_f32_e32 v114, v114, v115
	v_add_f32_e32 v145, v112, v114
	s_waitcnt vmcnt(11) lgkmcnt(3)
	v_pk_add_f32 v[116:117], v[116:117], v[28:29]
	v_pk_add_f32 v[118:119], v[118:119], v[30:31]
	global_store_dwordx4 v138, v[116:119], s[92:93] nt
	v_cvt_pk_bf16_f32 v28, v116, v117
	v_cvt_pk_bf16_f32 v29, v118, v119
	v_lshrrev_b32_e32 v30, 1, v138
	v_pk_mul_f32 v[116:117], v[116:117], v[116:117]
	v_pk_mul_f32 v[118:119], v[118:119], v[118:119]
	global_store_dwordx2 v30, v[28:29], s[20:21]
	v_add_f32_e32 v116, v116, v117
	v_add_f32_e32 v118, v118, v119
	v_add_f32_e32 v146, v116, v118
	s_waitcnt vmcnt(12) lgkmcnt(2)
	v_pk_add_f32 v[120:121], v[120:121], v[32:33]
	v_pk_add_f32 v[122:123], v[122:123], v[34:35]
	global_store_dwordx4 v139, v[120:123], s[92:93] nt
	v_cvt_pk_bf16_f32 v32, v120, v121
	v_cvt_pk_bf16_f32 v33, v122, v123
	v_lshrrev_b32_e32 v34, 1, v139
	v_pk_mul_f32 v[120:121], v[120:121], v[120:121]
	v_pk_mul_f32 v[122:123], v[122:123], v[122:123]
	global_store_dwordx2 v34, v[32:33], s[20:21]
	v_add_f32_e32 v120, v120, v121
	v_add_f32_e32 v122, v122, v123
	v_add_f32_e32 v147, v120, v122
	s_waitcnt vmcnt(13) lgkmcnt(1)
	v_pk_add_f32 v[124:125], v[124:125], v[36:37]
	v_pk_add_f32 v[126:127], v[126:127], v[38:39]
	global_store_dwordx4 v140, v[124:127], s[92:93] nt
	v_cvt_pk_bf16_f32 v36, v124, v125
	v_cvt_pk_bf16_f32 v37, v126, v127
	v_lshrrev_b32_e32 v38, 1, v140
	v_pk_mul_f32 v[124:125], v[124:125], v[124:125]
	v_pk_mul_f32 v[126:127], v[126:127], v[126:127]
	global_store_dwordx2 v38, v[36:37], s[20:21]
	v_add_f32_e32 v124, v124, v125
	v_add_f32_e32 v126, v126, v127
	v_add_f32_e32 v148, v124, v126
	s_waitcnt vmcnt(14) lgkmcnt(0)
	v_pk_add_f32 v[128:129], v[128:129], v[40:41]
	v_pk_add_f32 v[130:131], v[130:131], v[42:43]
	global_store_dwordx4 v141, v[128:131], s[92:93] nt
	v_cvt_pk_bf16_f32 v40, v128, v129
	v_cvt_pk_bf16_f32 v41, v130, v131
	v_lshrrev_b32_e32 v42, 1, v141
	v_pk_mul_f32 v[128:129], v[128:129], v[128:129]
	v_pk_mul_f32 v[130:131], v[130:131], v[130:131]
	global_store_dwordx2 v42, v[40:41], s[20:21]
	v_add_f32_e32 v128, v128, v129
	v_add_f32_e32 v130, v130, v131
	v_add_f32_e32 v149, v128, v130
	v_add_f32_dpp v142, v142, v142 quad_perm:[1,0,3,2] row_mask:0xf bank_mask:0xf bound_ctrl:1
	v_add_f32_dpp v143, v143, v143 quad_perm:[1,0,3,2] row_mask:0xf bank_mask:0xf bound_ctrl:1
	v_add_f32_dpp v144, v144, v144 quad_perm:[1,0,3,2] row_mask:0xf bank_mask:0xf bound_ctrl:1
	v_add_f32_dpp v145, v145, v145 quad_perm:[1,0,3,2] row_mask:0xf bank_mask:0xf bound_ctrl:1
	v_add_f32_dpp v146, v146, v146 quad_perm:[1,0,3,2] row_mask:0xf bank_mask:0xf bound_ctrl:1
	v_add_f32_dpp v147, v147, v147 quad_perm:[1,0,3,2] row_mask:0xf bank_mask:0xf bound_ctrl:1
	v_add_f32_dpp v148, v148, v148 quad_perm:[1,0,3,2] row_mask:0xf bank_mask:0xf bound_ctrl:1
	v_add_f32_dpp v149, v149, v149 quad_perm:[1,0,3,2] row_mask:0xf bank_mask:0xf bound_ctrl:1
	v_add_f32_dpp v142, v142, v142 quad_perm:[2,3,0,1] row_mask:0xf bank_mask:0xf bound_ctrl:1
	v_add_f32_dpp v143, v143, v143 quad_perm:[2,3,0,1] row_mask:0xf bank_mask:0xf bound_ctrl:1
	v_add_f32_dpp v144, v144, v144 quad_perm:[2,3,0,1] row_mask:0xf bank_mask:0xf bound_ctrl:1
	v_add_f32_dpp v145, v145, v145 quad_perm:[2,3,0,1] row_mask:0xf bank_mask:0xf bound_ctrl:1
	v_add_f32_dpp v146, v146, v146 quad_perm:[2,3,0,1] row_mask:0xf bank_mask:0xf bound_ctrl:1
	v_add_f32_dpp v147, v147, v147 quad_perm:[2,3,0,1] row_mask:0xf bank_mask:0xf bound_ctrl:1
	v_add_f32_dpp v148, v148, v148 quad_perm:[2,3,0,1] row_mask:0xf bank_mask:0xf bound_ctrl:1
	v_add_f32_dpp v149, v149, v149 quad_perm:[2,3,0,1] row_mask:0xf bank_mask:0xf bound_ctrl:1
	v_add_f32_dpp v142, v142, v142 row_half_mirror row_mask:0xf bank_mask:0xf bound_ctrl:1
	v_add_f32_dpp v143, v143, v143 row_half_mirror row_mask:0xf bank_mask:0xf bound_ctrl:1
	v_add_f32_dpp v144, v144, v144 row_half_mirror row_mask:0xf bank_mask:0xf bound_ctrl:1
	v_add_f32_dpp v145, v145, v145 row_half_mirror row_mask:0xf bank_mask:0xf bound_ctrl:1
	v_add_f32_dpp v146, v146, v146 row_half_mirror row_mask:0xf bank_mask:0xf bound_ctrl:1
	v_add_f32_dpp v147, v147, v147 row_half_mirror row_mask:0xf bank_mask:0xf bound_ctrl:1
	v_add_f32_dpp v148, v148, v148 row_half_mirror row_mask:0xf bank_mask:0xf bound_ctrl:1
	v_add_f32_dpp v149, v149, v149 row_half_mirror row_mask:0xf bank_mask:0xf bound_ctrl:1
	v_add_f32_dpp v142, v142, v142 row_mirror row_mask:0xf bank_mask:0xf bound_ctrl:1
	v_add_f32_dpp v143, v143, v143 row_mirror row_mask:0xf bank_mask:0xf bound_ctrl:1
	v_add_f32_dpp v144, v144, v144 row_mirror row_mask:0xf bank_mask:0xf bound_ctrl:1
	v_add_f32_dpp v145, v145, v145 row_mirror row_mask:0xf bank_mask:0xf bound_ctrl:1
	v_add_f32_dpp v146, v146, v146 row_mirror row_mask:0xf bank_mask:0xf bound_ctrl:1
	v_add_f32_dpp v147, v147, v147 row_mirror row_mask:0xf bank_mask:0xf bound_ctrl:1
	v_add_f32_dpp v148, v148, v148 row_mirror row_mask:0xf bank_mask:0xf bound_ctrl:1
	v_add_f32_dpp v149, v149, v149 row_mirror row_mask:0xf bank_mask:0xf bound_ctrl:1
	ds_bpermute_b32 v12, v182, v142
	ds_bpermute_b32 v16, v182, v143
	ds_bpermute_b32 v20, v182, v144
	ds_bpermute_b32 v24, v182, v145
	ds_bpermute_b32 v28, v182, v146
	ds_bpermute_b32 v32, v182, v147
	ds_bpermute_b32 v36, v182, v148
	ds_bpermute_b32 v40, v182, v149
	s_waitcnt lgkmcnt(0)
	v_add_f32_e32 v142, v142, v12
	v_add_f32_e32 v143, v143, v16
	v_add_f32_e32 v144, v144, v20
	v_add_f32_e32 v145, v145, v24
	v_add_f32_e32 v146, v146, v28
	v_add_f32_e32 v147, v147, v32
	v_add_f32_e32 v148, v148, v36
	v_add_f32_e32 v149, v149, v40
	v_add_u32_e32 v13, 0x200, v99
	v_add_u32_e32 v17, 0x240, v99
	v_add_u32_e32 v21, 0x280, v99
	v_add_u32_e32 v25, 0x2c0, v99
	v_add_u32_e32 v29, 0x300, v99
	v_add_u32_e32 v33, 0x340, v99
	v_add_u32_e32 v37, 0x380, v99
	v_add_u32_e32 v41, 0x3c0, v99
	s_mov_b64 exec, s[0:1]
	global_atomic_add_f32 v13, v142, s[50:51]
	global_atomic_add_f32 v17, v143, s[50:51]
	global_atomic_add_f32 v21, v144, s[50:51]
	global_atomic_add_f32 v25, v145, s[50:51]
	global_atomic_add_f32 v29, v146, s[50:51]
	global_atomic_add_f32 v33, v147, s[50:51]
	global_atomic_add_f32 v37, v148, s[50:51]
	global_atomic_add_f32 v41, v149, s[50:51]
	s_mov_b64 exec, -1
	s_branch .LBB0_158
.Lcepi_last:
	ds_read_b128 v[12:15], v61 offset:0
	v_mov_b32_e32 v134, v98
	global_load_dwordx4 v[100:103], v134, s[92:93] nt
	ds_read_b128 v[16:19], v61 offset:8448
	v_add_u32_e32 v135, 0x10000, v98
	global_load_dwordx4 v[104:107], v135, s[92:93] nt
	ds_read_b128 v[20:23], v61 offset:16896
	v_add_u32_e32 v136, 0x20000, v98
	global_load_dwordx4 v[108:111], v136, s[92:93] nt
	ds_read_b128 v[24:27], v61 offset:25344
	v_add_u32_e32 v137, 0x30000, v98
	global_load_dwordx4 v[112:115], v137, s[92:93] nt
	ds_read_b128 v[28:31], v61 offset:33792
	v_add_u32_e32 v138, 0x40000, v98
	global_load_dwordx4 v[116:119], v138, s[92:93] nt
	ds_read_b128 v[32:35], v61 offset:42240
	v_add_u32_e32 v139, 0x50000, v98
	global_load_dwordx4 v[120:123], v139, s[92:93] nt
	ds_read_b128 v[36:39], v61 offset:50688
	v_add_u32_e32 v140, 0x60000, v98
	global_load_dwordx4 v[124:127], v140, s[92:93] nt
	ds_read_b128 v[40:43], v61 offset:59136
	v_add_u32_e32 v141, 0x70000, v98
	global_load_dwordx4 v[128:131], v141, s[92:93] nt
	s_waitcnt vmcnt(7) lgkmcnt(7)
	v_pk_add_f32 v[100:101], v[100:101], v[12:13]
	v_pk_add_f32 v[102:103], v[102:103], v[14:15]
	global_store_dwordx4 v134, v[100:103], s[92:93] nt
	s_waitcnt vmcnt(7) lgkmcnt(6)
	v_pk_add_f32 v[104:105], v[104:105], v[16:17]
	v_pk_add_f32 v[106:107], v[106:107], v[18:19]
	global_store_dwordx4 v135, v[104:107], s[92:93] nt
	s_waitcnt vmcnt(7) lgkmcnt(5)
	v_pk_add_f32 v[108:109], v[108:109], v[20:21]
	v_pk_add_f32 v[110:111], v[110:111], v[22:23]
	global_store_dwordx4 v136, v[108:111], s[92:93] nt
	s_waitcnt vmcnt(7) lgkmcnt(4)
	v_pk_add_f32 v[112:113], v[112:113], v[24:25]
	v_pk_add_f32 v[114:115], v[114:115], v[26:27]
	global_store_dwordx4 v137, v[112:115], s[92:93] nt
	s_waitcnt vmcnt(7) lgkmcnt(3)
	v_pk_add_f32 v[116:117], v[116:117], v[28:29]
	v_pk_add_f32 v[118:119], v[118:119], v[30:31]
	global_store_dwordx4 v138, v[116:119], s[92:93] nt
	s_waitcnt vmcnt(7) lgkmcnt(2)
	v_pk_add_f32 v[120:121], v[120:121], v[32:33]
	v_pk_add_f32 v[122:123], v[122:123], v[34:35]
	global_store_dwordx4 v139, v[120:123], s[92:93] nt
	s_waitcnt vmcnt(7) lgkmcnt(1)
	v_pk_add_f32 v[124:125], v[124:125], v[36:37]
	v_pk_add_f32 v[126:127], v[126:127], v[38:39]
	global_store_dwordx4 v140, v[124:127], s[92:93] nt
	s_waitcnt vmcnt(7) lgkmcnt(0)
	v_pk_add_f32 v[128:129], v[128:129], v[40:41]
	v_pk_add_f32 v[130:131], v[130:131], v[42:43]
	global_store_dwordx4 v141, v[128:131], s[92:93] nt
	ds_read_b128 v[12:15], v62 offset:0
	v_add_u32_e32 v134, 0x80000, v98
	global_load_dwordx4 v[100:103], v134, s[92:93] nt
	ds_read_b128 v[16:19], v62 offset:8448
	v_add_u32_e32 v135, 0x90000, v98
	global_load_dwordx4 v[104:107], v135, s[92:93] nt
	ds_read_b128 v[20:23], v62 offset:16896
	v_add_u32_e32 v136, 0xa0000, v98
	global_load_dwordx4 v[108:111], v136, s[92:93] nt
	ds_read_b128 v[24:27], v62 offset:25344
	v_add_u32_e32 v137, 0xb0000, v98
	global_load_dwordx4 v[112:115], v137, s[92:93] nt
	ds_read_b128 v[28:31], v62 offset:33792
	v_add_u32_e32 v138, 0xc0000, v98
	global_load_dwordx4 v[116:119], v138, s[92:93] nt
	ds_read_b128 v[32:35], v62 offset:42240
	v_add_u32_e32 v139, 0xd0000, v98
	global_load_dwordx4 v[120:123], v139, s[92:93] nt
	ds_read_b128 v[36:39], v62 offset:50688
	v_add_u32_e32 v140, 0xe0000, v98
	global_load_dwordx4 v[124:127], v140, s[92:93] nt
	ds_read_b128 v[40:43], v62 offset:59136
	v_add_u32_e32 v141, 0xf0000, v98
	global_load_dwordx4 v[128:131], v141, s[92:93] nt
	s_waitcnt vmcnt(7) lgkmcnt(7)
	v_pk_add_f32 v[100:101], v[100:101], v[12:13]
	v_pk_add_f32 v[102:103], v[102:103], v[14:15]
	global_store_dwordx4 v134, v[100:103], s[92:93] nt
	s_waitcnt vmcnt(7) lgkmcnt(6)
	v_pk_add_f32 v[104:105], v[104:105], v[16:17]
	v_pk_add_f32 v[106:107], v[106:107], v[18:19]
	global_store_dwordx4 v135, v[104:107], s[92:93] nt
	s_waitcnt vmcnt(7) lgkmcnt(5)
	v_pk_add_f32 v[108:109], v[108:109], v[20:21]
	v_pk_add_f32 v[110:111], v[110:111], v[22:23]
	global_store_dwordx4 v136, v[108:111], s[92:93] nt
	s_waitcnt vmcnt(7) lgkmcnt(4)
	v_pk_add_f32 v[112:113], v[112:113], v[24:25]
	v_pk_add_f32 v[114:115], v[114:115], v[26:27]
	global_store_dwordx4 v137, v[112:115], s[92:93] nt
	s_waitcnt vmcnt(7) lgkmcnt(3)
	v_pk_add_f32 v[116:117], v[116:117], v[28:29]
	v_pk_add_f32 v[118:119], v[118:119], v[30:31]
	global_store_dwordx4 v138, v[116:119], s[92:93] nt
	s_waitcnt vmcnt(7) lgkmcnt(2)
	v_pk_add_f32 v[120:121], v[120:121], v[32:33]
	v_pk_add_f32 v[122:123], v[122:123], v[34:35]
	global_store_dwordx4 v139, v[120:123], s[92:93] nt
	s_waitcnt vmcnt(7) lgkmcnt(1)
	v_pk_add_f32 v[124:125], v[124:125], v[36:37]
	v_pk_add_f32 v[126:127], v[126:127], v[38:39]
	global_store_dwordx4 v140, v[124:127], s[92:93] nt
	s_waitcnt vmcnt(7) lgkmcnt(0)
	v_pk_add_f32 v[128:129], v[128:129], v[40:41]
	v_pk_add_f32 v[130:131], v[130:131], v[42:43]
	global_store_dwordx4 v141, v[128:131], s[92:93] nt
	s_branch .LBB0_158
